# P5: half of the workgroups (blockIdx bit 3) run the RG part before the head-norm so streaming and compute overlap across the chip
# baseline (speedup 1.0000x reference)
.LBB0_790:
	s_cmp_gt_i32 s64, 5
	s_cselect_b64 s[0:1], -1, 0
	s_cmp_lt_i32 s65, 6
	s_cselect_b64 s[2:3], -1, 0
	s_or_b64 s[0:1], s[2:3], s[0:1]
	s_and_b64 vcc, exec, s[0:1]
	s_cbranch_vccnz .LBB0_928
	s_mov_b32 s100, 0
	s_bitcmp1_b32 s66, 3
	s_cbranch_scc0 .Lp5_hn_entry
	s_mov_b32 s100, 1
	s_branch .LBB0_794
.Lp5_hn_entry:
	s_lshl_b32 s0, s66, 3
	s_add_i32 s0, s97, s0
	s_cmpk_gt_i32 s0, 0x3fff
	s_cbranch_scc1 .LBB0_794
	v_readlane_b32 s2, v250, 0
	v_readlane_b32 s3, v250, 1
	s_load_dwordx2 s[2:3], s[2:3], 0x78
	s_waitcnt vmcnt(0)
	v_lshlrev_b32_e32 v2, 6, v1
	v_and_b32_e32 v18, 0x1c0, v2
	s_ashr_i32 s1, s0, 31
	s_mul_i32 s4, s0, 0x3000
	s_waitcnt lgkmcnt(0)
	global_load_dwordx4 v[2:5], v18, s[2:3] offset:32
	global_load_dwordx4 v[6:9], v18, s[2:3] offset:48
	global_load_dwordx4 v[10:13], v18, s[2:3]
	global_load_dwordx4 v[14:17], v18, s[2:3] offset:16
	v_mbcnt_lo_u32_b32 v18, -1, 0
	v_mbcnt_hi_u32_b32 v18, -1, v18
	v_and_b32_e32 v20, 64, v18
	v_xor_b32_e32 v19, 1, v18
	v_add_u32_e32 v20, 64, v20
	v_cmp_lt_i32_e32 vcc, v19, v20
	s_lshl_b32 s2, s70, 3
	s_mul_hi_i32 s3, s0, 0x3000
	v_cndmask_b32_e32 v19, v18, v19, vcc
	v_lshlrev_b32_e32 v24, 2, v19
	v_xor_b32_e32 v19, 2, v18
	v_cmp_lt_i32_e32 vcc, v19, v20
	s_add_u32 s4, s74, s4
	s_addc_u32 s5, s75, s3
	v_cndmask_b32_e32 v19, v18, v19, vcc
	s_ashr_i32 s3, s2, 31
	s_lshl_b64 s[6:7], s[0:1], 12
	v_lshlrev_b32_e32 v25, 2, v19
	v_xor_b32_e32 v19, 4, v18
	s_add_u32 s1, s72, s6
	v_cmp_lt_i32_e32 vcc, v19, v20
	s_addc_u32 s7, s73, s7
	s_add_u32 s6, s1, 16
	v_cndmask_b32_e32 v18, v18, v19, vcc
	v_lshlrev_b32_e32 v26, 2, v18
	v_lshlrev_b32_e32 v18, 5, v1
	v_mov_b32_e32 v19, 0
	s_mul_i32 s16, s70, 0x18000
	s_mul_hi_i32 s17, s2, 0x3000
	s_addc_u32 s7, s7, 0
	s_lshl_b64 s[8:9], s[2:3], 12
	s_mov_b64 s[10:11], 0x39c4000
	s_mov_b64 s[12:13], 0x39c4800
	s_mov_b64 s[14:15], 0x39c5800
	s_mov_b32 s1, 0x39c5000
	v_mov_b32_e32 v27, 0x358637bd
	s_mov_b32 s3, 0x800000

.LBB0_794:
	s_cmp_eq_u32 s100, 2
	s_cbranch_scc1 .Lp5_end
	s_cmpk_gt_i32 s66, 0x3ff
	v_lshlrev_b32_e32 v160, 3, v0
	v_lshrrev_b32_e32 v133, 4, v1
	v_and_b32_e32 v130, 48, v1
	v_and_b32_e32 v159, 48, v0
	v_cmp_gt_u32_e64 s[4:5], 16, v1
	v_cmp_gt_u32_e64 s[6:7], 32, v1
	v_cmp_lt_u32_e64 s[8:9], 31, v1
	v_lshrrev_b32_e32 v158, 4, v0
	s_waitcnt vmcnt(0) lgkmcnt(0)
	s_barrier
	s_cbranch_scc1 .LBB0_819
	v_and_b32_e32 v6, 15, v0
	v_mov_b32_e32 v137, 0
	v_lshl_or_b32 v134, s97, 4, v6
	v_mov_b32_e32 v135, v137
	v_readlane_b32 s2, v250, 0
	v_lshlrev_b64 v[138:139], 8, v[134:135]
	v_readlane_b32 s3, v250, 1
	v_lshl_add_u64 v[2:3], s[74:75], 0, v[138:139]
	v_mov_b32_e32 v131, v137
	s_load_dwordx4 s[16:19], s[2:3], 0x80
	s_load_dwordx2 s[0:1], s[2:3], 0x98
	s_load_dwordx4 s[20:23], s[2:3], 0xa8
	v_lshl_add_u64 v[2:3], v[2:3], 0, v[130:131]
	s_mov_b64 s[2:3], 0xcc4000
	v_lshrrev_b32_e32 v5, 3, v0
	v_lshl_add_u64 v[140:141], v[2:3], 0, s[2:3]
	v_lshlrev_b32_e32 v2, 4, v6
	v_and_b32_e32 v161, 62, v5
	v_add_u32_e32 v3, 0, v2
	v_or_b32_e32 v5, 1, v5
	v_add_u32_e32 v2, v3, v2
	v_lshlrev_b32_e32 v8, 9, v161
	v_mul_u32_u24_e32 v9, 0x110, v5
	v_lshlrev_b32_e32 v5, 9, v5
	v_add_u32_e32 v165, v2, v8
	v_add_u32_e32 v167, v2, v5
	v_or_b32_e32 v22, 0x200, v0
	v_mbcnt_lo_u32_b32 v2, -1, 0
	v_and_b32_e32 v132, 0x78, v160
	v_lshlrev_b32_e32 v135, 11, v133
	v_lshrrev_b32_e32 v163, 4, v22
	v_mbcnt_hi_u32_b32 v2, -1, v2
	v_lshlrev_b32_e32 v4, 3, v133
	v_mul_u32_u24_e32 v7, 0x110, v161
	v_add_u32_e32 v10, 0, v159
	v_lshl_add_u32 v162, v134, 2, 0
	s_add_u32 s24, s74, 0xf9c4000
	v_mul_u32_u24_e32 v11, 0x110, v6
	v_or_b32_e32 v12, 0x4000, v135
	v_or_b32_e32 v13, 0x4200, v135
	v_or_b32_e32 v14, 0x4400, v135
	v_or_b32_e32 v15, 0x4600, v135
	v_or_b32_e32 v16, 0x6000, v135
	v_or_b32_e32 v17, 0x6200, v135
	v_or_b32_e32 v18, 0x6400, v135
	v_or_b32_e32 v19, 0x6600, v135
	v_lshl_add_u32 v20, v132, 2, 0
	v_lshlrev_b32_e32 v21, 9, v158
	v_lshlrev_b32_e32 v22, 9, v163
	v_and_or_b32 v2, v2, 64, v6
	v_lshlrev_b32_e32 v131, 3, v6
	s_mov_b32 s3, 0
	s_addc_u32 s25, s75, 0
	v_cmp_eq_u32_e64 s[10:11], 3, v133
	s_movk_i32 s33, 0x3000
	s_mov_b32 s42, 0x39c6000
	s_mov_b64 s[26:27], 0x1000
	s_movk_i32 s43, 0x1000
	s_mov_b64 s[28:29], 0x2000
	s_movk_i32 s44, 0x2000
	s_mov_b64 s[30:31], 0x3000
	v_add_u32_e32 v164, v3, v7
	v_add_u32_e32 v166, v3, v9
	v_add_u32_e32 v168, v10, v11
	v_lshlrev_b32_e32 v142, 1, v4
	s_mov_b64 s[34:35], 0xd04000
	s_mov_b32 s45, 0xd04000
	s_mov_b32 s46, 0xc1a00000
	s_mov_b32 s47, 0x3f2aaaab
	v_mov_b32_e32 v169, 0x3ecc95a3
	s_mov_b32 s48, 0x3f317218
	s_mov_b32 s49, 0x7f800000
	s_mov_b32 s50, 0x33800000
	v_add_u32_e32 v170, v162, v12
	v_add_u32_e32 v171, v162, v13
	v_add_u32_e32 v172, v162, v14
	v_add_u32_e32 v173, v162, v15
	v_add_u32_e32 v174, v162, v16
	v_add_u32_e32 v175, v162, v17
	v_add_u32_e32 v176, v162, v18
	v_add_u32_e32 v177, v162, v19
	v_add_u32_e32 v178, v20, v21
	v_add_u32_e32 v179, v20, v22
	v_mov_b32_e32 v144, 0x3f317218
	v_mov_b32_e32 v180, 0x7f800000
	v_mov_b32_e32 v181, 0x7fc00000
	v_mov_b32_e32 v182, 0xff800000
	v_lshlrev_b32_e32 v183, 2, v2
	s_mov_b32 s51, s66
	s_branch .LBB0_797

.LBB0_878:
	s_cmp_eq_u32 s100, 1
	s_cbranch_scc0 .Lp5_end
	s_mov_b32 s100, 2
	s_branch .Lp5_hn_entry
